# PV sections of all three attention loops: transposed-V read addresses from 8 lane bases plus immediate offsets
# speedup vs baseline: 1.0148x; 1.0075x over previous
.LBB0_629:
	v_add_u32_e32 v0, s26, v125
	v_add3_u32 v147, v0, v130, v131
	v_add3_u32 v165, v0, v130, v133
	v_add3_u32 v166, v0, v130, v140
	v_add3_u32 v167, v0, v130, v141
	v_add3_u32 v168, v0, v130, v142
	v_add3_u32 v169, v0, v130, v143
	v_add3_u32 v170, v0, v130, v144
	v_add3_u32 v0, v0, v130, v145
	ds_read_b64_tr_b16 v[82:83], v147
	ds_read_b64_tr_b16 v[84:85], v165 offset:2048
	ds_read_b64_tr_b16 v[86:87], v147 offset:4096
	ds_read_b64_tr_b16 v[88:89], v165 offset:6144
	ds_read_b64_tr_b16 v[90:91], v147 offset:8192
	ds_read_b64_tr_b16 v[92:93], v165 offset:10240
	ds_read_b64_tr_b16 v[94:95], v147 offset:12288
	ds_read_b64_tr_b16 v[96:97], v165 offset:14336
	ds_read_b64_tr_b16 v[148:149], v166
	ds_read_b64_tr_b16 v[150:151], v167 offset:2048
	ds_read_b64_tr_b16 v[152:153], v166 offset:4096
	ds_read_b64_tr_b16 v[154:155], v167 offset:6144
	ds_read_b64_tr_b16 v[156:157], v166 offset:8192
	ds_read_b64_tr_b16 v[158:159], v167 offset:10240
	ds_read_b64_tr_b16 v[160:161], v166 offset:12288
	ds_read_b64_tr_b16 v[162:163], v167 offset:14336
	s_waitcnt lgkmcnt(0)
	s_nop 0
	v_mfma_f32_32x32x16_bf16 v[50:65], v[82:85], v[74:77], v[50:65]
	v_mfma_f32_32x32x16_bf16 v[34:49], v[148:151], v[74:77], v[34:49]
	v_mfma_f32_32x32x16_bf16 v[50:65], v[86:89], v[78:81], v[50:65]
	v_mfma_f32_32x32x16_bf16 v[34:49], v[152:155], v[78:81], v[34:49]
	v_mfma_f32_32x32x16_bf16 v[50:65], v[90:93], v[66:69], v[50:65]
	v_mfma_f32_32x32x16_bf16 v[34:49], v[156:159], v[66:69], v[34:49]
	v_mfma_f32_32x32x16_bf16 v[50:65], v[94:97], v[70:73], v[50:65]
	v_mfma_f32_32x32x16_bf16 v[34:49], v[160:163], v[70:73], v[34:49]
	ds_read_b64_tr_b16 v[82:83], v168
	ds_read_b64_tr_b16 v[84:85], v169 offset:2048
	ds_read_b64_tr_b16 v[86:87], v168 offset:4096
	ds_read_b64_tr_b16 v[88:89], v169 offset:6144
	ds_read_b64_tr_b16 v[90:91], v168 offset:8192
	ds_read_b64_tr_b16 v[92:93], v169 offset:10240
	ds_read_b64_tr_b16 v[94:95], v168 offset:12288
	ds_read_b64_tr_b16 v[96:97], v169 offset:14336
	ds_read_b64_tr_b16 v[148:149], v170
	ds_read_b64_tr_b16 v[150:151], v0 offset:2048
	ds_read_b64_tr_b16 v[152:153], v170 offset:4096
	ds_read_b64_tr_b16 v[154:155], v0 offset:6144
	ds_read_b64_tr_b16 v[156:157], v170 offset:8192
	ds_read_b64_tr_b16 v[158:159], v0 offset:10240
	ds_read_b64_tr_b16 v[160:161], v170 offset:12288
	ds_read_b64_tr_b16 v[162:163], v0 offset:14336
	s_waitcnt lgkmcnt(0)
	v_mfma_f32_32x32x16_bf16 v[18:33], v[82:85], v[74:77], v[18:33]
	v_mfma_f32_32x32x16_bf16 v[2:17], v[148:151], v[74:77], v[2:17]
	v_mfma_f32_32x32x16_bf16 v[18:33], v[86:89], v[78:81], v[18:33]
	v_mfma_f32_32x32x16_bf16 v[2:17], v[152:155], v[78:81], v[2:17]
	v_mfma_f32_32x32x16_bf16 v[18:33], v[90:93], v[66:69], v[18:33]
	v_mfma_f32_32x32x16_bf16 v[2:17], v[156:159], v[66:69], v[2:17]
	v_mfma_f32_32x32x16_bf16 v[18:33], v[94:97], v[70:73], v[18:33]
	v_mfma_f32_32x32x16_bf16 v[2:17], v[160:163], v[70:73], v[2:17]
	v_mov_b32_e32 v147, v164
	s_andn2_b64 vcc, exec, s[2:3]
	s_mov_b64 s[2:3], -1
	s_cbranch_vccz .LBB0_631
	s_branch .LBB0_632

.LBB0_1179:
	v_add_u32_e32 v0, s12, v142
	v_add3_u32 v96, v0, v151, v152
	v_add3_u32 v97, v0, v151, v154
	v_add3_u32 v183, v0, v151, v177
	v_add3_u32 v188, v0, v151, v178
	v_add3_u32 v189, v0, v151, v179
	v_add3_u32 v190, v0, v151, v180
	v_add3_u32 v191, v0, v151, v181
	v_add3_u32 v0, v0, v151, v182
	ds_read_b64_tr_b16 v[84:85], v96
	ds_read_b64_tr_b16 v[86:87], v97 offset:2048
	ds_read_b64_tr_b16 v[88:89], v96 offset:4096
	ds_read_b64_tr_b16 v[90:91], v97 offset:6144
	ds_read_b64_tr_b16 v[92:93], v96 offset:8192
	ds_read_b64_tr_b16 v[94:95], v97 offset:10240
	ds_read_b64_tr_b16 v[160:161], v96 offset:12288
	ds_read_b64_tr_b16 v[162:163], v97 offset:14336
	ds_read_b64_tr_b16 v[164:165], v183
	ds_read_b64_tr_b16 v[166:167], v188 offset:2048
	ds_read_b64_tr_b16 v[168:169], v183 offset:4096
	ds_read_b64_tr_b16 v[170:171], v188 offset:6144
	ds_read_b64_tr_b16 v[172:173], v183 offset:8192
	ds_read_b64_tr_b16 v[174:175], v188 offset:10240
	ds_read_b64_tr_b16 v[184:185], v183 offset:12288
	ds_read_b64_tr_b16 v[186:187], v188 offset:14336
	s_waitcnt lgkmcnt(0)
	s_nop 0
	v_mfma_f32_32x32x16_bf16 v[50:65], v[84:87], v[74:77], v[50:65]
	v_mfma_f32_32x32x16_bf16 v[34:49], v[164:167], v[74:77], v[34:49]
	v_mfma_f32_32x32x16_bf16 v[50:65], v[88:91], v[78:81], v[50:65]
	v_mfma_f32_32x32x16_bf16 v[34:49], v[168:171], v[78:81], v[34:49]
	v_mfma_f32_32x32x16_bf16 v[50:65], v[92:95], v[66:69], v[50:65]
	v_mfma_f32_32x32x16_bf16 v[34:49], v[172:175], v[66:69], v[34:49]
	v_mfma_f32_32x32x16_bf16 v[50:65], v[160:163], v[70:73], v[50:65]
	v_mfma_f32_32x32x16_bf16 v[34:49], v[184:187], v[70:73], v[34:49]
	ds_read_b64_tr_b16 v[84:85], v189
	ds_read_b64_tr_b16 v[86:87], v190 offset:2048
	ds_read_b64_tr_b16 v[88:89], v189 offset:4096
	ds_read_b64_tr_b16 v[90:91], v190 offset:6144
	ds_read_b64_tr_b16 v[92:93], v189 offset:8192
	ds_read_b64_tr_b16 v[94:95], v190 offset:10240
	ds_read_b64_tr_b16 v[160:161], v189 offset:12288
	ds_read_b64_tr_b16 v[162:163], v190 offset:14336
	ds_read_b64_tr_b16 v[164:165], v191
	ds_read_b64_tr_b16 v[166:167], v0 offset:2048
	ds_read_b64_tr_b16 v[168:169], v191 offset:4096
	ds_read_b64_tr_b16 v[170:171], v0 offset:6144
	ds_read_b64_tr_b16 v[172:173], v191 offset:8192
	ds_read_b64_tr_b16 v[174:175], v0 offset:10240
	ds_read_b64_tr_b16 v[184:185], v191 offset:12288
	ds_read_b64_tr_b16 v[186:187], v0 offset:14336
	s_waitcnt lgkmcnt(0)
	v_mfma_f32_32x32x16_bf16 v[18:33], v[84:87], v[74:77], v[18:33]
	v_mfma_f32_32x32x16_bf16 v[2:17], v[164:167], v[74:77], v[2:17]
	v_mfma_f32_32x32x16_bf16 v[18:33], v[88:91], v[78:81], v[18:33]
	v_mfma_f32_32x32x16_bf16 v[2:17], v[168:171], v[78:81], v[2:17]
	v_mfma_f32_32x32x16_bf16 v[18:33], v[92:95], v[66:69], v[18:33]
	v_mfma_f32_32x32x16_bf16 v[2:17], v[172:175], v[66:69], v[2:17]
	v_mfma_f32_32x32x16_bf16 v[18:33], v[160:163], v[70:73], v[18:33]
	v_mfma_f32_32x32x16_bf16 v[2:17], v[184:187], v[70:73], v[2:17]
	v_mov_b32_e32 v183, v83
	s_andn2_b64 vcc, exec, s[0:1]
	s_mov_b64 s[0:1], -1
	s_cbranch_vccz .LBB0_1181
	s_branch .LBB0_1182

.LBB0_1193:
	v_add_u32_e32 v0, s15, v187
	v_add3_u32 v164, v0, v218, v219
	v_add3_u32 v165, v0, v218, v221
	v_add3_u32 v166, v0, v218, v228
	v_add3_u32 v167, v0, v218, v229
	v_add3_u32 v168, v0, v218, v230
	v_add3_u32 v169, v0, v218, v231
	v_add3_u32 v170, v0, v218, v232
	v_add3_u32 v0, v0, v218, v233
	ds_read_b64_tr_b16 v[84:85], v164
	ds_read_b64_tr_b16 v[86:87], v165 offset:2048
	ds_read_b64_tr_b16 v[88:89], v164 offset:4096
	ds_read_b64_tr_b16 v[90:91], v165 offset:6144
	ds_read_b64_tr_b16 v[92:93], v164 offset:8192
	ds_read_b64_tr_b16 v[94:95], v165 offset:10240
	ds_read_b64_tr_b16 v[96:97], v164 offset:12288
	ds_read_b64_tr_b16 v[98:99], v165 offset:14336
	ds_read_b64_tr_b16 v[100:101], v166
	ds_read_b64_tr_b16 v[102:103], v167 offset:2048
	ds_read_b64_tr_b16 v[104:105], v166 offset:4096
	ds_read_b64_tr_b16 v[106:107], v167 offset:6144
	ds_read_b64_tr_b16 v[108:109], v166 offset:8192
	ds_read_b64_tr_b16 v[110:111], v167 offset:10240
	ds_read_b64_tr_b16 v[160:161], v166 offset:12288
	ds_read_b64_tr_b16 v[162:163], v167 offset:14336
	s_waitcnt lgkmcnt(0)
	s_nop 0
	v_mfma_f32_32x32x16_bf16 v[64:79], v[84:87], v[10:13], v[64:79]
	v_mfma_f32_32x32x16_bf16 v[48:63], v[100:103], v[10:13], v[48:63]
	v_mfma_f32_32x32x16_bf16 v[64:79], v[88:91], v[80:83], v[64:79]
	v_mfma_f32_32x32x16_bf16 v[48:63], v[104:107], v[80:83], v[48:63]
	v_mfma_f32_32x32x16_bf16 v[64:79], v[92:95], v[2:5], v[64:79]
	v_mfma_f32_32x32x16_bf16 v[48:63], v[108:111], v[2:5], v[48:63]
	v_mfma_f32_32x32x16_bf16 v[64:79], v[96:99], v[6:9], v[64:79]
	v_mfma_f32_32x32x16_bf16 v[48:63], v[160:163], v[6:9], v[48:63]
	ds_read_b64_tr_b16 v[84:85], v168
	ds_read_b64_tr_b16 v[86:87], v169 offset:2048
	ds_read_b64_tr_b16 v[88:89], v168 offset:4096
	ds_read_b64_tr_b16 v[90:91], v169 offset:6144
	ds_read_b64_tr_b16 v[92:93], v168 offset:8192
	ds_read_b64_tr_b16 v[94:95], v169 offset:10240
	ds_read_b64_tr_b16 v[96:97], v168 offset:12288
	ds_read_b64_tr_b16 v[98:99], v169 offset:14336
	ds_read_b64_tr_b16 v[100:101], v170
	ds_read_b64_tr_b16 v[102:103], v0 offset:2048
	ds_read_b64_tr_b16 v[104:105], v170 offset:4096
	ds_read_b64_tr_b16 v[106:107], v0 offset:6144
	ds_read_b64_tr_b16 v[108:109], v170 offset:8192
	ds_read_b64_tr_b16 v[110:111], v0 offset:10240
	ds_read_b64_tr_b16 v[160:161], v170 offset:12288
	ds_read_b64_tr_b16 v[162:163], v0 offset:14336
	s_waitcnt lgkmcnt(0)
	v_mfma_f32_32x32x16_bf16 v[32:47], v[84:87], v[10:13], v[32:47]
	v_mfma_f32_32x32x16_bf16 v[16:31], v[100:103], v[10:13], v[16:31]
	v_mfma_f32_32x32x16_bf16 v[32:47], v[88:91], v[80:83], v[32:47]
	v_mfma_f32_32x32x16_bf16 v[16:31], v[104:107], v[80:83], v[16:31]
	v_mfma_f32_32x32x16_bf16 v[32:47], v[92:95], v[2:5], v[32:47]
	v_mfma_f32_32x32x16_bf16 v[16:31], v[108:111], v[2:5], v[16:31]
	v_mfma_f32_32x32x16_bf16 v[32:47], v[96:99], v[6:9], v[32:47]
	v_mfma_f32_32x32x16_bf16 v[16:31], v[160:163], v[6:9], v[16:31]
	v_mov_b32_e32 v234, v15
	s_andn2_b64 vcc, exec, s[12:13]
	s_mov_b64 s[12:13], -1
	s_cbranch_vccz .LBB0_1195
	s_branch .LBB0_1196
